# P0 rows loop: XN/PB stores sc1 (write-through) on top of x loads nt
# baseline (speedup 1.0000x reference)
.LBB0_38:
	s_add_i32 s28, s56, s58
	s_cmpk_lt_i32 s28, 0x4000
	s_cselect_b32 s16, s28, s56
	s_ashr_i32 s57, s56, 31
	s_lshl_b64 s[46:47], s[56:57], 12
	v_lshl_add_u64 v[34:35], v[2:3], 0, s[46:47]
	global_load_dwordx4 v[18:21], v[4:5], off
	s_ashr_i32 s17, s16, 31
	global_load_dwordx4 v[22:25], v[34:35], off nt
	global_load_dwordx4 v[26:29], v[34:35], off offset:1024 nt
	global_load_dwordx4 v[30:33], v[34:35], off offset:3072 nt
	s_nop 0
	global_load_dwordx4 v[34:37], v[34:35], off offset:2048 nt
	s_lshl_b64 s[0:1], s[56:57], 10
	s_lshl_b64 s[50:51], s[16:17], 12
	s_lshl_b64 s[46:47], s[16:17], 10
	v_lshl_add_u64 v[38:39], v[6:7], 0, s[0:1]
	v_lshl_add_u64 v[64:65], v[2:3], 0, s[50:51]
	global_load_dwordx4 v[38:41], v[38:39], off nt
	v_lshl_add_u64 v[66:67], v[6:7], 0, s[46:47]
	global_load_dwordx4 v[42:45], v[64:65], off nt
	global_load_dwordx4 v[46:49], v[64:65], off offset:1024 nt
	global_load_dwordx4 v[50:53], v[64:65], off offset:3072 nt
	global_load_dwordx4 v[54:57], v[64:65], off offset:2048 nt
	global_load_dwordx4 v[58:61], v[66:67], off nt
	s_lshl_b64 s[0:1], s[16:17], 11
	v_lshl_add_u64 v[68:69], v[8:9], 0, s[0:1]
	s_lshl_b64 s[48:49], s[56:57], 11
	v_lshl_add_u64 v[62:63], v[8:9], 0, s[48:49]
	s_waitcnt vmcnt(9)
	v_pk_mul_f32 v[64:65], v[24:25], v[24:25]
	v_pk_mul_f32 v[66:67], v[22:23], v[22:23]
	s_waitcnt vmcnt(8)
	v_pk_mul_f32 v[70:71], v[28:29], v[28:29]
	v_pk_mul_f32 v[72:73], v[26:27], v[26:27]
	s_waitcnt vmcnt(6)
	v_mul_f32_e32 v74, v35, v35
	v_mul_f32_e32 v76, v37, v37
	v_pk_mov_b32 v[78:79], v[66:67], v[64:65] op_sel:[1,0]
	v_mov_b32_e32 v67, v65
	s_waitcnt vmcnt(4)
	v_pk_mul_f32 v[64:65], v[44:45], v[44:45]
	v_pk_mul_f32 v[80:81], v[42:43], v[42:43]
	v_pk_mov_b32 v[82:83], v[72:73], v[70:71] op_sel:[1,0]
	v_mov_b32_e32 v73, v71
	s_waitcnt vmcnt(3)
	v_pk_mul_f32 v[70:71], v[48:49], v[48:49]
	v_pk_mul_f32 v[84:85], v[46:47], v[46:47]
	v_mul_f32_e32 v89, v32, v32
	v_mul_f32_e32 v90, v33, v33
	v_pk_fma_f32 v[74:75], v[34:35], v[34:35], v[74:75] op_sel_hi:[1,1,0]
	v_pk_fma_f32 v[76:77], v[36:37], v[36:37], v[76:77] op_sel_hi:[1,1,0]
	v_pk_add_f32 v[66:67], v[78:79], v[66:67]
	v_pk_mov_b32 v[78:79], v[80:81], v[64:65] op_sel:[1,0]
	v_mov_b32_e32 v81, v65
	v_pk_add_f32 v[64:65], v[82:83], v[72:73]
	v_pk_mov_b32 v[72:73], v[84:85], v[70:71] op_sel:[1,0]
	v_mov_b32_e32 v85, v71
	v_mul_f32_e32 v87, v31, v31
	s_waitcnt vmcnt(1)
	v_mul_f32_e32 v86, v55, v55
	v_mul_f32_e32 v88, v57, v57
	v_mov_b32_e32 v75, v89
	v_mov_b32_e32 v77, v90
	v_pk_add_f32 v[78:79], v[78:79], v[80:81]
	v_pk_add_f32 v[72:73], v[72:73], v[84:85]
	v_mul_f32_e32 v17, v30, v30
	v_mul_f32_e32 v91, v50, v50
	v_mul_f32_e32 v92, v51, v51
	v_mul_f32_e32 v93, v52, v52
	v_mul_f32_e32 v94, v53, v53
	v_pk_fma_f32 v[70:71], v[54:55], v[54:55], v[86:87] op_sel_hi:[1,1,0]
	v_pk_fma_f32 v[82:83], v[56:57], v[56:57], v[88:89] op_sel_hi:[1,1,0]
	v_pk_add_f32 v[66:67], v[66:67], v[66:67] op_sel:[0,1] op_sel_hi:[1,0]
	v_pk_add_f32 v[64:65], v[64:65], v[64:65] op_sel:[0,1] op_sel_hi:[1,0]
	v_pk_add_f32 v[74:75], v[74:75], v[76:77]
	v_pk_add_f32 v[76:77], v[78:79], v[78:79] op_sel:[0,1] op_sel_hi:[1,0]
	v_pk_add_f32 v[72:73], v[72:73], v[72:73] op_sel:[0,1] op_sel_hi:[1,0]
	v_mov_b32_e32 v71, v93
	v_mov_b32_e32 v83, v94
	v_mov_b32_e32 v67, v17
	v_mov_b32_e32 v65, v87
	v_mov_b32_e32 v77, v91
	v_mov_b32_e32 v73, v92
	v_pk_add_f32 v[70:71], v[70:71], v[82:83]
	v_pk_add_f32 v[64:65], v[66:67], v[64:65]
	v_pk_add_f32 v[66:67], v[76:77], v[72:73]
	v_pk_add_f32 v[64:65], v[64:65], v[74:75]
	v_pk_add_f32 v[66:67], v[66:67], v[70:71]
	v_mov_b32_e32 v71, v64
	v_mov_b32_e32 v70, v66
	v_mov_b32_e32 v64, v67
	v_pk_add_f32 v[64:65], v[70:71], v[64:65]
	ds_bpermute_b32 v67, v11, v65
	ds_bpermute_b32 v66, v11, v64
	s_waitcnt lgkmcnt(0)
	v_pk_add_f32 v[64:65], v[64:65], v[66:67]
	ds_bpermute_b32 v67, v12, v65
	ds_bpermute_b32 v66, v12, v64
	s_waitcnt lgkmcnt(0)
	v_pk_add_f32 v[64:65], v[64:65], v[66:67]
	ds_bpermute_b32 v67, v13, v65
	ds_bpermute_b32 v66, v13, v64
	s_waitcnt lgkmcnt(0)
	v_pk_add_f32 v[64:65], v[64:65], v[66:67]
	ds_bpermute_b32 v67, v14, v65
	ds_bpermute_b32 v66, v14, v64
	s_waitcnt lgkmcnt(0)
	v_pk_add_f32 v[64:65], v[64:65], v[66:67]
	ds_bpermute_b32 v67, v15, v65
	ds_bpermute_b32 v66, v15, v64
	s_waitcnt lgkmcnt(0)
	v_pk_add_f32 v[64:65], v[64:65], v[66:67]
	ds_bpermute_b32 v67, v16, v65
	ds_bpermute_b32 v66, v16, v64
	s_waitcnt lgkmcnt(0)
	v_pk_add_f32 v[64:65], v[64:65], v[66:67]
	s_nop 0
	v_pk_fma_f32 v[64:65], v[64:65], s[14:15], v[10:11] op_sel_hi:[1,0,0]
	s_nop 0
	v_mul_f32_e32 v17, 0x4b800000, v65
	v_cmp_gt_f32_e64 s[0:1], s15, v65
	v_mul_f32_e32 v66, 0x4b800000, v64
	v_cmp_gt_f32_e32 vcc, s15, v64
	v_cndmask_b32_e64 v17, v65, v17, s[0:1]
	v_rsq_f32_e32 v17, v17
	v_cndmask_b32_e32 v64, v64, v66, vcc
	v_rsq_f32_e32 v65, v64
	v_mul_f32_e32 v64, 0x45800000, v17
	v_cndmask_b32_e64 v64, v17, v64, s[0:1]
	v_mul_f32_e32 v66, 0x45800000, v65
	v_cndmask_b32_e32 v66, v65, v66, vcc
	v_pk_mul_f32 v[22:23], v[64:65], v[22:23] op_sel_hi:[0,1]
	v_pk_mul_f32 v[24:25], v[64:65], v[24:25] op_sel_hi:[0,1]
	v_pk_mul_f32 v[42:43], v[66:67], v[42:43] op_sel_hi:[0,1]
	v_pk_mul_f32 v[44:45], v[66:67], v[44:45] op_sel_hi:[0,1]
	v_pk_mul_f32 v[24:25], v[24:25], v[20:21]
	v_pk_mul_f32 v[22:23], v[22:23], v[18:19]
	v_pk_mul_f32 v[20:21], v[44:45], v[20:21]
	v_pk_mul_f32 v[18:19], v[42:43], v[18:19]
	v_cvt_pk_bf16_f32 v22, v22, v23
	v_cvt_pk_bf16_f32 v23, v24, v25
	v_cvt_pk_bf16_f32 v18, v18, v19
	v_cvt_pk_bf16_f32 v19, v20, v21
	global_store_dwordx2 v[62:63], v[22:23], off sc1
	global_store_dwordx2 v[68:69], v[18:19], off sc1
	global_load_dwordx4 v[18:21], v[4:5], off offset:1024
	v_pk_mul_f32 v[22:23], v[64:65], v[26:27] op_sel_hi:[0,1]
	v_pk_mul_f32 v[24:25], v[64:65], v[28:29] op_sel_hi:[0,1]
	v_pk_mul_f32 v[26:27], v[66:67], v[46:47] op_sel_hi:[0,1]
	v_pk_mul_f32 v[28:29], v[66:67], v[48:49] op_sel_hi:[0,1]
	s_lshl_b64 s[0:1], s[56:57], 9
	v_pk_mul_f32 v[30:31], v[64:65], v[30:31] op_sel_hi:[0,1]
	v_pk_mul_f32 v[32:33], v[64:65], v[32:33] op_sel_hi:[0,1]
	s_add_i32 s56, s28, s58
	s_waitcnt vmcnt(0)
	v_pk_mul_f32 v[24:25], v[24:25], v[20:21]
	v_pk_mul_f32 v[22:23], v[22:23], v[18:19]
	v_pk_mul_f32 v[20:21], v[28:29], v[20:21]
	v_pk_mul_f32 v[18:19], v[26:27], v[18:19]
	v_cvt_pk_bf16_f32 v22, v22, v23
	v_cvt_pk_bf16_f32 v23, v24, v25
	v_cvt_pk_bf16_f32 v18, v18, v19
	v_cvt_pk_bf16_f32 v19, v20, v21
	global_store_dwordx2 v[62:63], v[22:23], off offset:512 sc1
	global_store_dwordx2 v[68:69], v[18:19], off offset:512 sc1
	global_load_dwordx4 v[18:21], v[4:5], off offset:2048
	v_pk_mul_f32 v[22:23], v[64:65], v[34:35] op_sel_hi:[0,1]
	v_pk_mul_f32 v[24:25], v[64:65], v[36:37] op_sel_hi:[0,1]
	v_pk_mul_f32 v[26:27], v[66:67], v[54:55] op_sel_hi:[0,1]
	v_pk_mul_f32 v[28:29], v[66:67], v[56:57] op_sel_hi:[0,1]
	v_pk_mul_f32 v[34:35], v[66:67], v[50:51] op_sel_hi:[0,1]
	v_pk_mul_f32 v[36:37], v[66:67], v[52:53] op_sel_hi:[0,1]
	s_waitcnt vmcnt(0)
	v_pk_mul_f32 v[24:25], v[24:25], v[20:21]
	v_pk_mul_f32 v[22:23], v[22:23], v[18:19]
	v_pk_mul_f32 v[20:21], v[28:29], v[20:21]
	v_pk_mul_f32 v[18:19], v[26:27], v[18:19]
	v_cvt_pk_bf16_f32 v22, v22, v23
	v_cvt_pk_bf16_f32 v23, v24, v25
	v_cvt_pk_bf16_f32 v18, v18, v19
	v_cvt_pk_bf16_f32 v19, v20, v21
	global_store_dwordx2 v[62:63], v[22:23], off offset:1024 sc1
	global_store_dwordx2 v[68:69], v[18:19], off offset:1024 sc1
	global_load_dwordx4 v[18:21], v[4:5], off offset:3072
	v_lshl_add_u64 v[22:23], v[0:1], 0, s[0:1]
	s_lshl_b64 s[0:1], s[16:17], 9
	s_cmpk_gt_i32 s56, 0x3fff
	v_lshl_add_u64 v[24:25], v[0:1], 0, s[0:1]
	v_cvt_pk_bf16_f32 v26, v38, v39
	v_cvt_pk_bf16_f32 v27, v40, v41
	v_cvt_pk_bf16_f32 v28, v58, v59
	v_cvt_pk_bf16_f32 v29, v60, v61
	s_waitcnt vmcnt(0)
	v_pk_mul_f32 v[32:33], v[32:33], v[20:21]
	v_pk_mul_f32 v[30:31], v[30:31], v[18:19]
	v_pk_mul_f32 v[20:21], v[36:37], v[20:21]
	v_pk_mul_f32 v[18:19], v[34:35], v[18:19]
	v_cvt_pk_bf16_f32 v30, v30, v31
	v_cvt_pk_bf16_f32 v31, v32, v33
	v_cvt_pk_bf16_f32 v18, v18, v19
	v_cvt_pk_bf16_f32 v19, v20, v21
	global_store_dwordx2 v[62:63], v[30:31], off offset:1536 sc1
	global_store_dwordx2 v[68:69], v[18:19], off offset:1536 sc1
	global_store_dwordx2 v[22:23], v[26:27], off sc1
	global_store_dwordx2 v[24:25], v[28:29], off sc1
	s_cbranch_scc0 .LBB0_38
